# gemm_out epilogue: gate load issued before the staging barrier into v250-253 (was after the barrier, waited immediately)
# speedup vs baseline: 1.0039x; 1.0039x over previous
; __device__ void phase_gemm_out(const Params& p, int bid, int nb, char* lds, const TileMap& tm) {
;     ...
;     for (int j = 0; j < 2; ++j)
; #pragma unroll
;       for (int i = 0; i < 2; ++i) {
;         const int rl = 64 * wm + 32 * i + l31;
;         const float rb = rbv[rl];
; #pragma unroll
;         for (int g = 0; g < 4; ++g) {
;           const f32x16& a = acc[j][i];
;           *(float4*)(stf + rl * 132 + 64 * wn + 32 * j + 8 * g + 4 * h) = make_float4(a[4 * g] * rb, a[4 * g + 1] * rb, a[4 * g + 2] * rb, a[4 * g + 3] * rb);
;         }
;       }
;     __syncthreads();
;     const int b = m0 >> 13;
;     const float* gate = ada + b * 6144 + 2048 + n0;
;     {
;       const int c32 = tid & 31, r0 = tid >> 5;
;       const float4 gt = *(const float4*)(gate + c32 * 4);
; #pragma unroll
;       for (int q = 0; q < 16; ++q) {
;         const int row = r0 + 8 * q;
;         const size_t idx = (size_t)(m0 + row) * 1024 + n0 + c32 * 4;
;         const float4 xv = *(const float4*)(p.x + idx);
.LBB0_310:
	v_add_u32_e32 v248, s45, v79
	v_or_b32_e32 v249, s0, v66
	v_lshl_add_u32 v248, v248, 10, v249
	v_lshlrev_b32_e32 v248, 2, v248
	global_load_dwordx4 v[184:187], v248, s[72:73]
	v_add_u32_e32 v248, 0x8000, v248
	global_load_dwordx4 v[188:191], v248, s[72:73]
	v_add_u32_e32 v248, 0x8000, v248
	global_load_dwordx4 v[192:195], v248, s[72:73]
	v_add_u32_e32 v248, 0x8000, v248
	global_load_dwordx4 v[196:199], v248, s[72:73]
	v_add_u32_e32 v248, 0x8000, v248
	global_load_dwordx4 v[200:203], v248, s[72:73]
	v_add_u32_e32 v248, 0x8000, v248
	global_load_dwordx4 v[204:207], v248, s[72:73]
	v_add_u32_e32 v248, 0x8000, v248
	global_load_dwordx4 v[208:211], v248, s[72:73]
	v_add_u32_e32 v248, 0x8000, v248
	global_load_dwordx4 v[212:215], v248, s[72:73]
	v_add_u32_e32 v248, 0x8000, v248
	global_load_dwordx4 v[216:219], v248, s[72:73]
	v_add_u32_e32 v248, 0x8000, v248
	global_load_dwordx4 v[220:223], v248, s[72:73]
	v_add_u32_e32 v248, 0x8000, v248
	global_load_dwordx4 v[224:227], v248, s[72:73]
	v_add_u32_e32 v248, 0x8000, v248
	global_load_dwordx4 v[228:231], v248, s[72:73]
	v_add_u32_e32 v248, 0x8000, v248
	global_load_dwordx4 v[232:235], v248, s[72:73]
	v_add_u32_e32 v248, 0x8000, v248
	global_load_dwordx4 v[236:239], v248, s[72:73]
	v_add_u32_e32 v248, 0x8000, v248
	global_load_dwordx4 v[240:243], v248, s[72:73]
	v_add_u32_e32 v248, 0x8000, v248
	global_load_dwordx4 v[244:247], v248, s[72:73]
	s_setprio 0
	ds_read_b32 v0, v80
	s_lshr_b32 s1, s44, 6
	s_mul_i32 s40, s1, 0x1800
	s_ashr_i32 s41, s40, 31
	s_lshl_b64 s[40:41], s[40:41], 2
	s_waitcnt lgkmcnt(0)
	v_pk_mul_f32 v[50:51], v[50:51], v[0:1] op_sel_hi:[1,0]
	v_pk_mul_f32 v[52:53], v[52:53], v[0:1] op_sel_hi:[1,0]
	v_pk_mul_f32 v[54:55], v[54:55], v[0:1] op_sel_hi:[1,0]
	v_pk_mul_f32 v[56:57], v[56:57], v[0:1] op_sel_hi:[1,0]
	ds_write_b128 v82, v[50:53]
	ds_write_b128 v82, v[54:57] offset:32
	v_pk_mul_f32 v[50:51], v[58:59], v[0:1] op_sel_hi:[1,0]
	v_pk_mul_f32 v[52:53], v[60:61], v[0:1] op_sel_hi:[1,0]
	ds_write_b128 v82, v[50:53] offset:64
	v_pk_mul_f32 v[50:51], v[62:63], v[0:1] op_sel_hi:[1,0]
	v_pk_mul_f32 v[52:53], v[64:65], v[0:1] op_sel_hi:[1,0]
	ds_write_b128 v82, v[50:53] offset:96
	ds_read_b32 v0, v81
	s_add_u32 s42, s92, s40
	s_addc_u32 s43, s93, s41
	s_ashr_i32 s1, s0, 31
	s_lshl_b64 s[40:41], s[0:1], 2
	s_waitcnt lgkmcnt(0)
	v_pk_mul_f32 v[34:35], v[34:35], v[0:1] op_sel_hi:[1,0]
	v_pk_mul_f32 v[36:37], v[36:37], v[0:1] op_sel_hi:[1,0]
	ds_write_b128 v82, v[34:37] offset:16896
	v_pk_mul_f32 v[34:35], v[38:39], v[0:1] op_sel_hi:[1,0]
	v_pk_mul_f32 v[36:37], v[40:41], v[0:1] op_sel_hi:[1,0]
	ds_write_b128 v82, v[34:37] offset:16928
	v_pk_mul_f32 v[34:35], v[42:43], v[0:1] op_sel_hi:[1,0]
	v_pk_mul_f32 v[36:37], v[44:45], v[0:1] op_sel_hi:[1,0]
	ds_write_b128 v82, v[34:37] offset:16960
	v_pk_mul_f32 v[34:35], v[46:47], v[0:1] op_sel_hi:[1,0]
	v_pk_mul_f32 v[36:37], v[48:49], v[0:1] op_sel_hi:[1,0]
	ds_write_b128 v82, v[34:37] offset:16992
	ds_read_b32 v0, v80
	s_add_u32 s40, s42, s40
	s_addc_u32 s41, s43, s41
	s_add_i32 s21, s21, 1
	s_waitcnt lgkmcnt(0)
	v_pk_mul_f32 v[18:19], v[18:19], v[0:1] op_sel_hi:[1,0]
	v_pk_mul_f32 v[20:21], v[20:21], v[0:1] op_sel_hi:[1,0]
	ds_write_b128 v82, v[18:21] offset:128
	v_pk_mul_f32 v[18:19], v[22:23], v[0:1] op_sel_hi:[1,0]
	v_pk_mul_f32 v[20:21], v[24:25], v[0:1] op_sel_hi:[1,0]
	ds_write_b128 v82, v[18:21] offset:160
	v_pk_mul_f32 v[18:19], v[26:27], v[0:1] op_sel_hi:[1,0]
	v_pk_mul_f32 v[20:21], v[28:29], v[0:1] op_sel_hi:[1,0]
	ds_write_b128 v82, v[18:21] offset:192
	v_pk_mul_f32 v[18:19], v[30:31], v[0:1] op_sel_hi:[1,0]
	v_pk_mul_f32 v[20:21], v[32:33], v[0:1] op_sel_hi:[1,0]
	ds_write_b128 v82, v[18:21] offset:224
	ds_read_b32 v0, v81
	s_waitcnt lgkmcnt(0)
	v_pk_mul_f32 v[2:3], v[2:3], v[0:1] op_sel_hi:[1,0]
	v_pk_mul_f32 v[4:5], v[4:5], v[0:1] op_sel_hi:[1,0]
	ds_write_b128 v82, v[2:5] offset:17024
	v_pk_mul_f32 v[2:3], v[6:7], v[0:1] op_sel_hi:[1,0]
	v_pk_mul_f32 v[4:5], v[8:9], v[0:1] op_sel_hi:[1,0]
	ds_write_b128 v82, v[2:5] offset:17056
	v_pk_mul_f32 v[2:3], v[10:11], v[0:1] op_sel_hi:[1,0]
	v_pk_mul_f32 v[4:5], v[12:13], v[0:1] op_sel_hi:[1,0]
	v_add_u32_e32 v8, s45, v79
	ds_write_b128 v82, v[2:5] offset:17088
	v_pk_mul_f32 v[2:3], v[14:15], v[0:1] op_sel_hi:[1,0]
	v_pk_mul_f32 v[4:5], v[16:17], v[0:1] op_sel_hi:[1,0]
	v_lshlrev_b32_e32 v0, 2, v66
	v_ashrrev_i32_e32 v9, 31, v8
	ds_write_b128 v82, v[2:5] offset:17120
	v_lshl_add_u64 v[2:3], s[40:41], 0, v[0:1]
	v_mov_b32_e32 v7, s1
	v_or_b32_e32 v6, s0, v66
	v_lshlrev_b64 v[4:5], 10, v[8:9]
	s_movk_i32 s0, 0x2000
	v_lshl_add_u64 v[4:5], v[4:5], 0, v[6:7]
	v_add_co_u32_e32 v2, vcc, s0, v2
	v_lshlrev_b64 v[18:19], 2, v[4:5]
	s_nop 0
	v_addc_co_u32_e32 v3, vcc, 0, v3, vcc
	global_load_dwordx4 v[250:253], v[2:3], off
	s_waitcnt lgkmcnt(0)
	s_barrier
; __device__ void phase_gemm_out(const Params& p, int bid, int nb, char* lds, const TileMap& tm) {
;     ...
;       const int c32 = tid & 31, r0 = tid >> 5;
;       const float4 gt = *(const float4*)(gate + c32 * 4);
; #pragma unroll
;       for (int q = 0; q < 16; ++q) {
;         const int row = r0 + 8 * q;
;         const size_t idx = (size_t)(m0 + row) * 1024 + n0 + c32 * 4;
;         const float4 xv = *(const float4*)(p.x + idx);
;         const float4 mv = *(const float4*)(stf + row * 132 + c32 * 4);
;         *(float4*)(p.out + idx) = make_float4(ALPHA * xv.x + gt.x * mv.x, ALPHA * xv.y + gt.y * mv.y, ALPHA * xv.z + gt.z * mv.z, ALPHA * xv.w + gt.w * mv.w);
;       }
	v_lshl_add_u64 v[10:11], s[72:73], 0, v[18:19]
	v_add_u32_e32 v14, 8, v8
	v_ashrrev_i32_e32 v15, 31, v14
	v_lshlrev_b64 v[14:15], 10, v[14:15]
	v_lshl_add_u64 v[20:21], v[14:15], 0, v[6:7]
	ds_read_b128 v[14:17], v83
	v_lshlrev_b64 v[22:23], 2, v[20:21]
	v_lshl_add_u64 v[24:25], s[90:91], 0, v[18:19]
	ds_read_b128 v[18:21], v83 offset:4224
	v_lshl_add_u64 v[26:27], s[72:73], 0, v[22:23]
	s_mov_b64 s[40:41], 0
	s_waitcnt vmcnt(0) lgkmcnt(1)
	v_pk_mul_f32 v[14:15], v[250:251], v[14:15]
	v_pk_mul_f32 v[16:17], v[252:253], v[16:17]
	s_waitcnt vmcnt(15)
	v_pk_fma_f32 v[10:11], v[184:185], s[34:35], v[14:15] op_sel_hi:[1,0,1]
	v_pk_fma_f32 v[12:13], v[186:187], s[34:35], v[16:17] op_sel_hi:[1,0,1]
	global_store_dwordx4 v[24:25], v[10:13], off
	v_add_u32_e32 v14, 16, v8
	v_ashrrev_i32_e32 v15, 31, v14
	v_lshlrev_b64 v[14:15], 10, v[14:15]
	v_lshl_add_u64 v[14:15], v[14:15], 0, v[6:7]
	s_waitcnt lgkmcnt(0)
	v_pk_mul_f32 v[18:19], v[250:251], v[18:19]
	v_pk_mul_f32 v[20:21], v[252:253], v[20:21]
	v_lshlrev_b64 v[24:25], 2, v[14:15]
	v_lshl_add_u64 v[14:15], s[90:91], 0, v[22:23]
	v_lshl_add_u64 v[16:17], s[72:73], 0, v[24:25]
	v_lshl_add_u64 v[24:25], s[90:91], 0, v[24:25]
	s_waitcnt vmcnt(15)
	v_pk_fma_f32 v[10:11], v[188:189], s[34:35], v[18:19] op_sel_hi:[1,0,1]
	v_pk_fma_f32 v[12:13], v[190:191], s[34:35], v[20:21] op_sel_hi:[1,0,1]
	global_store_dwordx4 v[14:15], v[10:13], off
	v_add_u32_e32 v14, 24, v8
	v_ashrrev_i32_e32 v15, 31, v14
	v_lshlrev_b64 v[14:15], 10, v[14:15]
	v_lshl_add_u64 v[18:19], v[14:15], 0, v[6:7]
	ds_read_b128 v[14:17], v83 offset:8448
	v_lshlrev_b64 v[22:23], 2, v[18:19]
	ds_read_b128 v[18:21], v83 offset:12672
	v_lshl_add_u64 v[26:27], s[72:73], 0, v[22:23]
	s_waitcnt lgkmcnt(1)
	v_pk_mul_f32 v[14:15], v[250:251], v[14:15]
	v_pk_mul_f32 v[16:17], v[252:253], v[16:17]
	s_waitcnt lgkmcnt(0)
	v_pk_mul_f32 v[18:19], v[250:251], v[18:19]
	v_pk_mul_f32 v[20:21], v[252:253], v[20:21]
	s_waitcnt vmcnt(15)
	v_pk_fma_f32 v[10:11], v[192:193], s[34:35], v[14:15] op_sel_hi:[1,0,1]
	v_pk_fma_f32 v[12:13], v[194:195], s[34:35], v[16:17] op_sel_hi:[1,0,1]
	global_store_dwordx4 v[24:25], v[10:13], off
	v_add_u32_e32 v14, 32, v8
	v_ashrrev_i32_e32 v15, 31, v14
	v_lshlrev_b64 v[14:15], 10, v[14:15]
	v_lshl_add_u64 v[14:15], v[14:15], 0, v[6:7]
	v_lshlrev_b64 v[24:25], 2, v[14:15]
	v_lshl_add_u64 v[14:15], s[90:91], 0, v[22:23]
	v_lshl_add_u64 v[16:17], s[72:73], 0, v[24:25]
	v_lshl_add_u64 v[24:25], s[90:91], 0, v[24:25]
	s_waitcnt vmcnt(15)
	v_pk_fma_f32 v[10:11], v[196:197], s[34:35], v[18:19] op_sel_hi:[1,0,1]
	v_pk_fma_f32 v[12:13], v[198:199], s[34:35], v[20:21] op_sel_hi:[1,0,1]
	global_store_dwordx4 v[14:15], v[10:13], off
	v_add_u32_e32 v14, 40, v8
	v_ashrrev_i32_e32 v15, 31, v14
	v_lshlrev_b64 v[14:15], 10, v[14:15]
	v_lshl_add_u64 v[18:19], v[14:15], 0, v[6:7]
	ds_read_b128 v[14:17], v83 offset:16896
	v_lshlrev_b64 v[22:23], 2, v[18:19]
	ds_read_b128 v[18:21], v83 offset:21120
	v_lshl_add_u64 v[26:27], s[72:73], 0, v[22:23]
	s_waitcnt lgkmcnt(1)
	v_pk_mul_f32 v[14:15], v[250:251], v[14:15]
	v_pk_mul_f32 v[16:17], v[252:253], v[16:17]
	s_waitcnt lgkmcnt(0)
	v_pk_mul_f32 v[18:19], v[250:251], v[18:19]
	v_pk_mul_f32 v[20:21], v[252:253], v[20:21]
	s_waitcnt vmcnt(15)
	v_pk_fma_f32 v[10:11], v[200:201], s[34:35], v[14:15] op_sel_hi:[1,0,1]
	v_pk_fma_f32 v[12:13], v[202:203], s[34:35], v[16:17] op_sel_hi:[1,0,1]
	global_store_dwordx4 v[24:25], v[10:13], off
	v_add_u32_e32 v14, 48, v8
	v_ashrrev_i32_e32 v15, 31, v14
	v_lshlrev_b64 v[14:15], 10, v[14:15]
	v_lshl_add_u64 v[14:15], v[14:15], 0, v[6:7]
	v_lshlrev_b64 v[24:25], 2, v[14:15]
	v_lshl_add_u64 v[14:15], s[90:91], 0, v[22:23]
	v_lshl_add_u64 v[16:17], s[72:73], 0, v[24:25]
	v_lshl_add_u64 v[24:25], s[90:91], 0, v[24:25]
	s_waitcnt vmcnt(15)
	v_pk_fma_f32 v[10:11], v[204:205], s[34:35], v[18:19] op_sel_hi:[1,0,1]
	v_pk_fma_f32 v[12:13], v[206:207], s[34:35], v[20:21] op_sel_hi:[1,0,1]
	global_store_dwordx4 v[14:15], v[10:13], off
	v_add_u32_e32 v14, 56, v8
	v_ashrrev_i32_e32 v15, 31, v14
	v_lshlrev_b64 v[14:15], 10, v[14:15]
	v_lshl_add_u64 v[18:19], v[14:15], 0, v[6:7]
	ds_read_b128 v[14:17], v83 offset:25344
	v_lshlrev_b64 v[22:23], 2, v[18:19]
	ds_read_b128 v[18:21], v83 offset:29568
	v_lshl_add_u64 v[26:27], s[72:73], 0, v[22:23]
	s_waitcnt lgkmcnt(1)
	v_pk_mul_f32 v[14:15], v[250:251], v[14:15]
	v_pk_mul_f32 v[16:17], v[252:253], v[16:17]
	s_waitcnt lgkmcnt(0)
	v_pk_mul_f32 v[18:19], v[250:251], v[18:19]
	v_pk_mul_f32 v[20:21], v[252:253], v[20:21]
	s_waitcnt vmcnt(15)
	v_pk_fma_f32 v[10:11], v[208:209], s[34:35], v[14:15] op_sel_hi:[1,0,1]
	v_pk_fma_f32 v[12:13], v[210:211], s[34:35], v[16:17] op_sel_hi:[1,0,1]
	global_store_dwordx4 v[24:25], v[10:13], off
	v_add_u32_e32 v14, 64, v8
	v_ashrrev_i32_e32 v15, 31, v14
	v_lshlrev_b64 v[14:15], 10, v[14:15]
	v_lshl_add_u64 v[14:15], v[14:15], 0, v[6:7]
	v_lshlrev_b64 v[24:25], 2, v[14:15]
	v_lshl_add_u64 v[14:15], s[90:91], 0, v[22:23]
	v_lshl_add_u64 v[16:17], s[72:73], 0, v[24:25]
	v_lshl_add_u64 v[24:25], s[90:91], 0, v[24:25]
	s_waitcnt vmcnt(15)
; __device__ void phase_gemm_out(const Params& p, int bid, int nb, char* lds, const TileMap& tm) {
;     ...
; #pragma unroll
;       for (int q = 0; q < 16; ++q) {
;         const int row = r0 + 8 * q;
;         const size_t idx = (size_t)(m0 + row) * 1024 + n0 + c32 * 4;
;         const float4 xv = *(const float4*)(p.x + idx);
;         const float4 mv = *(const float4*)(stf + row * 132 + c32 * 4);
;         *(float4*)(p.out + idx) = make_float4(ALPHA * xv.x + gt.x * mv.x, ALPHA * xv.y + gt.y * mv.y, ALPHA * xv.z + gt.z * mv.z, ALPHA * xv.w + gt.w * mv.w);
;       }
;     }
;     __syncthreads();
	v_pk_fma_f32 v[10:11], v[212:213], s[34:35], v[18:19] op_sel_hi:[1,0,1]
	v_pk_fma_f32 v[12:13], v[214:215], s[34:35], v[20:21] op_sel_hi:[1,0,1]
	global_store_dwordx4 v[14:15], v[10:13], off
	v_add_u32_e32 v14, 0x48, v8
	v_ashrrev_i32_e32 v15, 31, v14
	v_lshlrev_b64 v[14:15], 10, v[14:15]
	v_lshl_add_u64 v[18:19], v[14:15], 0, v[6:7]
	ds_read_b128 v[14:17], v83 offset:33792
	v_lshlrev_b64 v[22:23], 2, v[18:19]
	ds_read_b128 v[18:21], v83 offset:38016
	v_lshl_add_u64 v[26:27], s[72:73], 0, v[22:23]
	s_waitcnt lgkmcnt(1)
	v_pk_mul_f32 v[14:15], v[250:251], v[14:15]
	v_pk_mul_f32 v[16:17], v[252:253], v[16:17]
	s_waitcnt lgkmcnt(0)
	v_pk_mul_f32 v[18:19], v[250:251], v[18:19]
	v_pk_mul_f32 v[20:21], v[252:253], v[20:21]
	s_waitcnt vmcnt(15)
	v_pk_fma_f32 v[10:11], v[216:217], s[34:35], v[14:15] op_sel_hi:[1,0,1]
	v_pk_fma_f32 v[12:13], v[218:219], s[34:35], v[16:17] op_sel_hi:[1,0,1]
	global_store_dwordx4 v[24:25], v[10:13], off
	v_add_u32_e32 v14, 0x50, v8
	v_ashrrev_i32_e32 v15, 31, v14
	v_lshlrev_b64 v[14:15], 10, v[14:15]
	v_lshl_add_u64 v[14:15], v[14:15], 0, v[6:7]
	v_lshlrev_b64 v[24:25], 2, v[14:15]
	v_lshl_add_u64 v[14:15], s[90:91], 0, v[22:23]
	v_lshl_add_u64 v[16:17], s[72:73], 0, v[24:25]
	v_lshl_add_u64 v[24:25], s[90:91], 0, v[24:25]
	s_waitcnt vmcnt(15)
	v_pk_fma_f32 v[10:11], v[220:221], s[34:35], v[18:19] op_sel_hi:[1,0,1]
	v_pk_fma_f32 v[12:13], v[222:223], s[34:35], v[20:21] op_sel_hi:[1,0,1]
	global_store_dwordx4 v[14:15], v[10:13], off
	v_add_u32_e32 v14, 0x58, v8
	v_ashrrev_i32_e32 v15, 31, v14
	v_lshlrev_b64 v[14:15], 10, v[14:15]
	v_lshl_add_u64 v[18:19], v[14:15], 0, v[6:7]
	ds_read_b128 v[14:17], v83 offset:42240
	v_lshlrev_b64 v[22:23], 2, v[18:19]
	ds_read_b128 v[18:21], v83 offset:46464
	v_lshl_add_u64 v[26:27], s[72:73], 0, v[22:23]
	s_waitcnt lgkmcnt(1)
	v_pk_mul_f32 v[14:15], v[250:251], v[14:15]
	v_pk_mul_f32 v[16:17], v[252:253], v[16:17]
	s_waitcnt lgkmcnt(0)
	v_pk_mul_f32 v[18:19], v[250:251], v[18:19]
	v_pk_mul_f32 v[20:21], v[252:253], v[20:21]
	s_waitcnt vmcnt(15)
	v_pk_fma_f32 v[10:11], v[224:225], s[34:35], v[14:15] op_sel_hi:[1,0,1]
	v_pk_fma_f32 v[12:13], v[226:227], s[34:35], v[16:17] op_sel_hi:[1,0,1]
	global_store_dwordx4 v[24:25], v[10:13], off
	v_add_u32_e32 v14, 0x60, v8
	v_ashrrev_i32_e32 v15, 31, v14
	v_lshlrev_b64 v[14:15], 10, v[14:15]
	v_lshl_add_u64 v[14:15], v[14:15], 0, v[6:7]
	v_lshlrev_b64 v[24:25], 2, v[14:15]
	v_lshl_add_u64 v[14:15], s[90:91], 0, v[22:23]
	v_lshl_add_u64 v[16:17], s[72:73], 0, v[24:25]
	v_lshl_add_u64 v[24:25], s[90:91], 0, v[24:25]
	s_waitcnt vmcnt(15)
	v_pk_fma_f32 v[10:11], v[228:229], s[34:35], v[18:19] op_sel_hi:[1,0,1]
	v_pk_fma_f32 v[12:13], v[230:231], s[34:35], v[20:21] op_sel_hi:[1,0,1]
	global_store_dwordx4 v[14:15], v[10:13], off
	v_add_u32_e32 v14, 0x68, v8
	v_ashrrev_i32_e32 v15, 31, v14
	v_lshlrev_b64 v[14:15], 10, v[14:15]
	v_lshl_add_u64 v[18:19], v[14:15], 0, v[6:7]
	ds_read_b128 v[14:17], v83 offset:50688
	v_lshlrev_b64 v[22:23], 2, v[18:19]
	ds_read_b128 v[18:21], v83 offset:54912
	v_lshl_add_u64 v[26:27], s[72:73], 0, v[22:23]
	s_waitcnt lgkmcnt(1)
	v_pk_mul_f32 v[14:15], v[250:251], v[14:15]
	v_pk_mul_f32 v[16:17], v[252:253], v[16:17]
	s_waitcnt lgkmcnt(0)
	v_pk_mul_f32 v[18:19], v[250:251], v[18:19]
	v_pk_mul_f32 v[20:21], v[252:253], v[20:21]
	s_waitcnt vmcnt(15)
	v_pk_fma_f32 v[10:11], v[232:233], s[34:35], v[14:15] op_sel_hi:[1,0,1]
	v_pk_fma_f32 v[12:13], v[234:235], s[34:35], v[16:17] op_sel_hi:[1,0,1]
	global_store_dwordx4 v[24:25], v[10:13], off
	v_add_u32_e32 v14, 0x70, v8
	v_ashrrev_i32_e32 v15, 31, v14
	v_lshlrev_b64 v[14:15], 10, v[14:15]
	v_lshl_add_u64 v[14:15], v[14:15], 0, v[6:7]
	v_lshlrev_b64 v[14:15], 2, v[14:15]
	v_lshl_add_u64 v[16:17], s[90:91], 0, v[22:23]
	v_lshl_add_u64 v[22:23], s[72:73], 0, v[14:15]
	v_add_u32_e32 v8, 0x78, v8
	v_ashrrev_i32_e32 v9, 31, v8
	v_lshlrev_b64 v[8:9], 10, v[8:9]
	s_waitcnt vmcnt(15)
	v_pk_fma_f32 v[10:11], v[236:237], s[34:35], v[18:19] op_sel_hi:[1,0,1]
	v_pk_fma_f32 v[12:13], v[238:239], s[34:35], v[20:21] op_sel_hi:[1,0,1]
	global_store_dwordx4 v[16:17], v[10:13], off
	v_lshl_add_u64 v[16:17], v[8:9], 0, v[6:7]
	ds_read_b128 v[6:9], v83 offset:59136
	v_lshlrev_b64 v[18:19], 2, v[16:17]
	v_lshl_add_u64 v[20:21], s[90:91], 0, v[14:15]
	ds_read_b128 v[14:17], v83 offset:63360
	v_lshl_add_u64 v[22:23], s[72:73], 0, v[18:19]
	s_waitcnt lgkmcnt(1)
	v_pk_mul_f32 v[6:7], v[250:251], v[6:7]
	v_pk_mul_f32 v[8:9], v[252:253], v[8:9]
	s_waitcnt lgkmcnt(0)
	v_pk_mul_f32 v[2:3], v[250:251], v[14:15]
	v_pk_mul_f32 v[4:5], v[252:253], v[16:17]
	s_waitcnt vmcnt(15)
	v_pk_fma_f32 v[6:7], v[240:241], s[34:35], v[6:7] op_sel_hi:[1,0,1]
	v_pk_fma_f32 v[8:9], v[242:243], s[34:35], v[8:9] op_sel_hi:[1,0,1]
	global_store_dwordx4 v[20:21], v[6:9], off
	v_lshl_add_u64 v[10:11], s[90:91], 0, v[18:19]
	s_waitcnt vmcnt(15)
	v_pk_fma_f32 v[2:3], v[244:245], s[34:35], v[2:3] op_sel_hi:[1,0,1]
	v_pk_fma_f32 v[4:5], v[246:247], s[34:35], v[4:5] op_sel_hi:[1,0,1]
	global_store_dwordx4 v[10:11], v[2:5], off
	s_barrier
